# P5: late w_up copy on the four-tile GEMM workgroups only
# speedup vs baseline: 1.0065x; 1.0065x over previous
; #define LAS __attribute__((address_space(3)))
; #define MK_TID() ({ int w_ = wid0, z_ = 0; asm volatile("" : "+s"(w_), "+s"(z_)); w_ * 64 + (int)__builtin_amdgcn_mbcnt_hi(~0u, __builtin_amdgcn_mbcnt_lo(~0u, (unsigned)z_)); })
; __global__ void __launch_bounds__(512, 2) mk_fwd(Args a_) {
;     ...
;         } else if (ph == 5) {
;             const int tid = MK_TID(), lane = tid & 63, wid = __builtin_amdgcn_readfirstlane(tid >> 6);
;             LAS float* scr = (LAS float*)(lds + wid * 16384);
;             if (G > 2 * NML) { if (bid >= NML) {
; #pragma nounroll
;                 for (int it = (bid - NML) * 8 + wid; it < 11264; it += (G - NML) * 8) tr_mat_item(a, 10, it, scr, lane); } }
;             else {
; #pragma nounroll
;                 for (int it = bid * 8 + wid; it < 11264; it += G * 8) tr_mat_item(a, 10, it, scr, lane); }
.LBB0_770:
	s_andn2_b64 vcc, exec, s[18:19]
	s_cbranch_vccnz .LBB0_786
	v_readlane_b32 s6, v254, 36
	v_readlane_b32 s7, v254, 37
	s_andn2_b64 vcc, exec, s[6:7]
	s_cbranch_vccnz .LBB0_786
	s_cmpk_lt_i32 s56, 0xc8
	s_cbranch_scc1 .Lwu_even
	s_sub_i32 s6, s34, 0xa0
	s_cmp_lt_i32 s6, 0
	s_cbranch_scc1 .LBB0_786
	s_lshl_b32 s6, s6, 3
	s_add_i32 s5, s6, s5
	s_sub_i32 s68, s56, 0xa0
	s_lshl_b32 s68, s68, 3
	s_branch .Lwu_go
.Lwu_even:
	s_lshl_b32 s6, s34, 3
	s_add_i32 s5, s6, s5
	s_addk_i32 s5, 0xff00
.Lwu_go:
	s_cmpk_gt_i32 s5, 0x2bff
	s_cbranch_scc1 .LBB0_786
	s_load_dwordx4 s[44:47], s[0:1], 0xd8
	s_waitcnt lgkmcnt(0)
	v_and_b32_e32 v3, 7, v39
	v_readlane_b32 s6, v254, 30
	v_lshrrev_b32_e32 v2, 3, v43
	v_lshlrev_b32_e32 v0, 4, v3
	v_readlane_b32 s7, v254, 31
	v_lshl_add_u64 v[34:35], s[46:47], 0, v[0:1]
	s_cmp_lg_u64 s[44:45], 0
	v_add_u32_e32 v4, s4, v0
	v_mul_u32_u24_e32 v5, 0x84, v2
	v_mul_u32_u24_e32 v3, 0x420, v3
	v_lshl_add_u64 v[36:37], s[6:7], 0, v[0:1]
	v_lshlrev_b32_e32 v0, 2, v2
	s_cselect_b64 s[18:19], -1, 0
	v_add3_u32 v39, s4, v3, v0
	v_mov_b32_e32 v0, v2
	s_lshl_b32 s4, s5, 5
	s_lshl_b32 s6, s68, 5
	v_add_u32_e32 v43, v4, v5
	s_branch .LBB0_775

; #define LAS __attribute__((address_space(3)))
; #define MK_TID() ({ int w_ = wid0, z_ = 0; asm volatile("" : "+s"(w_), "+s"(z_)); w_ * 64 + (int)__builtin_amdgcn_mbcnt_hi(~0u, __builtin_amdgcn_mbcnt_lo(~0u, (unsigned)z_)); })
; __global__ void __launch_bounds__(512, 2) mk_fwd(Args a_) {
;     ...
;         } else if (ph == 5) {
;             const int tid = MK_TID(), lane = tid & 63, wid = __builtin_amdgcn_readfirstlane(tid >> 6);
;             LAS float* scr = (LAS float*)(lds + wid * 16384);
;             if (G > 2 * NML) { if (bid >= NML) {
; #pragma nounroll
;                 for (int it = (bid - NML) * 8 + wid; it < 11264; it += (G - NML) * 8) tr_mat_item(a, 10, it, scr, lane); } }
;             else {
; #pragma nounroll
;                 for (int it = bid * 8 + wid; it < 11264; it += G * 8) tr_mat_item(a, 10, it, scr, lane); }
;         }
.LBB0_786:
	v_readlane_b32 s68, v253, 60
	s_andn2_b64 vcc, exec, s[16:17]
	s_cbranch_vccnz .LBB0_788
	s_cmp_eq_u32 s91, 2
	s_cselect_b64 s[14:15], -1, 0

; __global__ void __launch_bounds__(512, 2) mk_fwd(Args a_) {
;     ...
;         if (ph + 1 < ph_hi) { if (ph >= 1000) grid.sync(); else xcd_barrier(xbar); }
;     }
.Lpost_getpc0:
	s_add_u32 s98, s98, (.LBB0_7-.Lpost_getpc0)&4294967295
	s_addc_u32 s99, s99, (.LBB0_7-.Lpost_getpc0)>>32
	s_setpc_b64 s[98:99]
	s_nop 0
	s_nop 0
	s_nop 0
	s_nop 0
	s_nop 0
	s_nop 0
	s_nop 0
	s_nop 0
	s_nop 0
	s_nop 0
	s_nop 0
	s_nop 0
	s_nop 0
	s_nop 0
	s_nop 0
	s_nop 0
	s_nop 0
	s_nop 0
	s_nop 0
	s_nop 0
	s_nop 0
	s_nop 0
	s_nop 0
	s_nop 0
	s_nop 0
	s_nop 0
	s_nop 0
	s_nop 0
	s_nop 0
	s_nop 0
	s_nop 0
	s_nop 0
	s_nop 0
	s_nop 0
	s_nop 0
	s_nop 0
	s_nop 0
	s_nop 0
	s_nop 0
	s_nop 0
	s_nop 0
	s_nop 0
	s_nop 0
	s_nop 0
	s_nop 0
	s_nop 0
	s_nop 0
	s_nop 0
	s_nop 0
	s_nop 0
	s_nop 0
	s_nop 0
	s_nop 0
	s_nop 0
	s_nop 0
	s_nop 0
	s_nop 0
	s_nop 0
	s_nop 0
	s_nop 0
	s_nop 0
	s_nop 0
	s_nop 0
	s_nop 0
	s_nop 0
	s_nop 0
	s_nop 0
	s_nop 0
	s_nop 0
	s_nop 0
	s_nop 0
	s_nop 0
	s_nop 0
	s_nop 0
	s_nop 0
	s_nop 0
	s_nop 0
	s_nop 0
	s_nop 0
	s_nop 0
	s_nop 0
	s_nop 0
	s_nop 0
	s_nop 0
	s_nop 0
	s_nop 0
	s_nop 0
	s_nop 0
	s_nop 0
	s_nop 0
	s_nop 0
	s_nop 0
	s_nop 0
	s_nop 0
	s_nop 0
	s_nop 0
	s_nop 0
	s_nop 0
	s_nop 0
	s_nop 0
	s_nop 0
	s_nop 0
	s_nop 0
	s_nop 0
	s_nop 0
	s_nop 0
	s_nop 0
	s_nop 0
	s_nop 0
	s_nop 0
	s_nop 0
	s_nop 0
	s_nop 0
	s_nop 0
	s_nop 0
	s_nop 0
	s_nop 0
	s_nop 0
	s_nop 0
	s_nop 0
	s_nop 0
	s_nop 0
	s_nop 0
	s_nop 0
	s_nop 0
	s_nop 0
	s_nop 0
	s_nop 0
	s_nop 0
	s_nop 0
	s_nop 0
	s_nop 0
	s_nop 0
	s_nop 0
	s_nop 0
	s_nop 0
	s_nop 0
	s_nop 0
	s_nop 0
	s_nop 0
	s_nop 0
	s_nop 0
	s_nop 0
	s_nop 0
	s_nop 0
	s_nop 0
	s_nop 0
	s_nop 0
	s_nop 0
	s_nop 0
	s_nop 0
	s_nop 0
	s_nop 0
	s_nop 0
	s_nop 0
	s_nop 0
	s_nop 0
	s_nop 0
	s_nop 0
	s_nop 0
	s_nop 0
	s_nop 0
	s_nop 0
	s_nop 0
	s_nop 0
	s_nop 0
	s_nop 0
	s_nop 0
	s_nop 0
	s_nop 0
	s_nop 0
	s_nop 0
	s_nop 0
	s_nop 0
	s_nop 0
	s_nop 0
	s_nop 0
	s_nop 0
	s_nop 0
	s_nop 0
	s_nop 0
	s_nop 0
	s_nop 0
	s_nop 0
	s_nop 0
	s_nop 0
	s_nop 0
	s_nop 0
	s_nop 0
	s_nop 0
	s_nop 0
	s_nop 0
	s_nop 0
	s_nop 0
	s_nop 0
	s_nop 0
	s_nop 0
	s_nop 0
	s_nop 0
	s_nop 0
	s_nop 0
	s_nop 0
	s_nop 0
	s_nop 0
	s_nop 0
	s_nop 0
	s_nop 0
	s_nop 0
	s_nop 0
	s_nop 0
	s_nop 0
	s_nop 0
	s_nop 0
	s_nop 0
	s_nop 0
	s_nop 0
	s_nop 0
	s_nop 0
	s_nop 0
	s_nop 0
	s_nop 0
	s_nop 0
	s_nop 0
	s_nop 0
	s_nop 0
	s_nop 0
	s_nop 0
	s_nop 0
	s_nop 0
	s_nop 0
	s_nop 0
	s_nop 0
	s_nop 0
	s_nop 0
	s_nop 0
	s_nop 0
	s_nop 0
	s_nop 0
	s_nop 0
	s_nop 0
	s_nop 0
	s_nop 0
	s_nop 0
	s_nop 0
	s_nop 0
	s_nop 0
	s_nop 0
	s_nop 0
	s_nop 0
	s_nop 0
	s_nop 0
	s_nop 0
	s_nop 0
	s_nop 0
	s_nop 0
	s_nop 0
	s_nop 0
	s_nop 0
	s_nop 0
	s_nop 0
	s_nop 0
	s_nop 0
	s_nop 0
	s_nop 0
	s_nop 0
	s_nop 0
	s_nop 0
	s_nop 0
	s_nop 0
	s_nop 0
	s_nop 0
	s_nop 0
	s_nop 0
	s_nop 0
	s_nop 0
	s_nop 0
	s_nop 0
	s_nop 0
	s_nop 0
	s_nop 0
	s_nop 0
	s_nop 0
	s_nop 0
	s_nop 0
	s_nop 0
	s_nop 0
	s_nop 0
	s_nop 0
	s_nop 0
	s_nop 0
	s_nop 0
	s_nop 0
	s_nop 0
	s_nop 0
	s_nop 0
	s_nop 0
	s_nop 0
	s_nop 0
	s_nop 0
	s_nop 0
	s_nop 0
	s_nop 0
	s_nop 0
	s_nop 0
	s_nop 0
	s_nop 0
	s_nop 0
	s_nop 0
	s_nop 0
	s_nop 0
	s_nop 0
	s_nop 0
	s_nop 0
	s_nop 0
	s_nop 0
	s_nop 0
	s_nop 0
	s_nop 0
	s_nop 0
	s_nop 0
	s_nop 0
	s_nop 0
	s_nop 0
	s_nop 0
	s_nop 0
	s_nop 0
	s_nop 0
	s_nop 0
	s_nop 0
	s_nop 0
	s_nop 0
	s_nop 0
	s_nop 0
	s_nop 0
	s_nop 0
	s_nop 0
	s_nop 0
	s_nop 0
	s_nop 0
	s_nop 0
	s_nop 0
	s_nop 0
	s_nop 0
	s_nop 0
	s_nop 0
	s_nop 0
	s_nop 0
	s_nop 0
	s_nop 0
	s_nop 0
	s_nop 0
	s_nop 0
	s_nop 0
	s_nop 0
	s_nop 0
	s_nop 0
	s_nop 0
	s_nop 0
	s_nop 0
	s_nop 0
	s_nop 0
	s_nop 0
	s_nop 0
	s_nop 0
	s_nop 0
	s_nop 0
	s_nop 0
	s_nop 0
	s_nop 0
	s_nop 0
	s_nop 0
	s_nop 0
	s_nop 0
	s_nop 0
	s_nop 0
	s_nop 0
	s_nop 0
	s_nop 0
	s_nop 0
	s_nop 0
	s_nop 0
	s_nop 0
	s_nop 0
	s_nop 0
	s_nop 0
	s_nop 0
	s_nop 0
	s_nop 0
	s_nop 0
	s_nop 0
	s_nop 0
	s_nop 0
	s_nop 0
	s_nop 0
	s_nop 0
	s_nop 0
	s_nop 0
	s_nop 0
	s_nop 0
	s_nop 0
	s_nop 0
	s_nop 0
	s_nop 0
	s_nop 0
	s_nop 0
	s_nop 0
	s_nop 0
	s_nop 0
	s_nop 0
	s_nop 0
	s_nop 0
	s_nop 0
	s_nop 0
	s_nop 0
	s_nop 0
	s_nop 0
	s_nop 0
	s_nop 0
	s_nop 0
	s_nop 0
	s_nop 0
	s_nop 0
	s_nop 0
	s_nop 0
	s_nop 0
	s_nop 0
	s_nop 0
	s_nop 0
	s_nop 0
	s_nop 0
	s_nop 0
	s_nop 0
	s_nop 0
	s_nop 0
	s_nop 0
	s_nop 0
	s_nop 0
	s_nop 0
	s_nop 0
	s_nop 0
	s_nop 0
	s_nop 0
	s_nop 0
	s_nop 0
	s_nop 0
	s_nop 0
	s_nop 0
	s_nop 0
	s_nop 0
	s_nop 0
	s_nop 0
	s_nop 0
	s_nop 0
	s_nop 0
	s_nop 0
	s_nop 0
	s_nop 0
	s_nop 0
	s_nop 0
	s_nop 0
	s_nop 0
	s_nop 0
	s_nop 0
	s_nop 0
	s_nop 0
	s_nop 0
	s_nop 0
	s_nop 0
	s_nop 0
	s_nop 0
	s_nop 0
	s_nop 0
	s_nop 0
	s_nop 0
	s_nop 0
	s_nop 0
	s_nop 0
	s_nop 0
	s_nop 0
	s_nop 0
	s_nop 0
	s_nop 0
	s_nop 0
	s_nop 0
	s_nop 0
.LBB0_1140:
	s_endpgm
